# prep: per-row gain multiply deferred to the LDS-write point so all 8 loads of a weight tile stay in flight (no vmcnt(0) between them)
# speedup vs baseline: 1.0295x; 1.0113x over previous
.LBB0_837:
	s_or_b64 exec, exec, s[14:15]
	s_cmp_lg_u64 s[20:21], 0
	s_cselect_b64 s[22:23], -1, 0
	s_cmp_eq_u64 s[20:21], 0
	v_mov_b32_e32 v100, 1.0
	s_cbranch_scc1 .LBB0_839
	v_lshl_add_u64 v[6:7], v[6:7], 2, s[20:21]
	global_load_dword v100, v[6:7], off

.LBB0_841:
	s_or_b64 exec, exec, s[14:15]
	v_cndmask_b32_e64 v1, 0, 1, s[22:23]
	v_cmp_ne_u32_e64 s[14:15], 1, v1
	s_andn2_b64 vcc, exec, s[22:23]
	v_mov_b32_e32 v102, 1.0
	s_cbranch_vccnz .LBB0_843
	v_lshl_add_u64 v[10:11], v[10:11], 2, s[20:21]
	global_load_dword v102, v[10:11], off

.LBB0_845:
	s_or_b64 exec, exec, s[22:23]
	s_and_b64 vcc, exec, s[14:15]
	v_mov_b32_e32 v104, 1.0
	s_cbranch_vccnz .LBB0_847
	v_lshl_add_u64 v[14:15], v[14:15], 2, s[20:21]
	global_load_dword v104, v[14:15], off

.LBB0_849:
	s_or_b64 exec, exec, s[22:23]
	s_and_b64 vcc, exec, s[14:15]
	v_mov_b32_e32 v106, 1.0
	s_cbranch_vccnz .LBB0_851
	v_lshl_add_u64 v[18:19], v[20:21], 2, s[20:21]
	global_load_dword v106, v[18:19], off

.LBB0_854:
	s_load_dwordx2 s[10:11], s[0:1], 0xb4
	s_mov_b32 s34, s18
	s_waitcnt vmcnt(0)
	v_pk_mul_f32 v[2:3], v[2:3], v[100:101] op_sel_hi:[1,0]
	v_pk_mul_f32 v[4:5], v[4:5], v[100:101] op_sel_hi:[1,0]
	v_pk_mul_f32 v[6:7], v[6:7], v[102:103] op_sel_hi:[1,0]
	v_pk_mul_f32 v[8:9], v[8:9], v[102:103] op_sel_hi:[1,0]
	v_pk_mul_f32 v[10:11], v[10:11], v[104:105] op_sel_hi:[1,0]
	v_pk_mul_f32 v[12:13], v[12:13], v[104:105] op_sel_hi:[1,0]
	v_pk_mul_f32 v[14:15], v[14:15], v[106:107] op_sel_hi:[1,0]
	v_pk_mul_f32 v[16:17], v[16:17], v[106:107] op_sel_hi:[1,0]
	ds_write2_b32 v29, v2, v3 offset1:1
	s_waitcnt lgkmcnt(0)
	ds_write2_b32 v29, v4, v5 offset0:2 offset1:3
	s_waitcnt lgkmcnt(0)
	ds_write2_b32 v30, v6, v7 offset1:1
	ds_write2_b32 v30, v8, v9 offset0:2 offset1:3
	ds_write2_b32 v31, v10, v11 offset1:1
	ds_write2_b32 v31, v12, v13 offset0:2 offset1:3
	ds_write2_b32 v32, v14, v15 offset1:1
	ds_write2_b32 v32, v16, v17 offset0:2 offset1:3
	s_waitcnt lgkmcnt(0)
	s_barrier
	s_add_i32 s27, s27, s11
	s_cmpk_gt_i32 s27, 0x51a3
	s_cselect_b64 s[14:15], -1, 0
	s_and_b64 vcc, exec, s[14:15]
	s_cbranch_vccnz .LBB0_853
	s_mov_b32 s25, 0
	s_mov_b32 s31, 0
	s_mov_b32 s36, s27
	s_mov_b32 s34, 0
	s_branch .LBB0_857

.LBB0_888:
	s_or_b64 exec, exec, s[12:13]
	s_cmp_lg_u64 s[22:23], 0
	s_cselect_b64 s[24:25], -1, 0
	s_cmp_eq_u64 s[22:23], 0
	v_mov_b32_e32 v100, 1.0
	s_cbranch_scc1 .LBB0_890
	v_lshl_add_u64 v[6:7], v[6:7], 2, s[22:23]
	global_load_dword v100, v[6:7], off

.LBB0_892:
	s_or_b64 exec, exec, s[12:13]
	v_cndmask_b32_e64 v1, 0, 1, s[24:25]
	v_cmp_ne_u32_e64 s[12:13], 1, v1
	s_andn2_b64 vcc, exec, s[24:25]
	v_mov_b32_e32 v102, 1.0
	s_cbranch_vccnz .LBB0_894
	v_lshl_add_u64 v[10:11], v[10:11], 2, s[22:23]
	global_load_dword v102, v[10:11], off

.LBB0_896:
	s_or_b64 exec, exec, s[24:25]
	s_and_b64 vcc, exec, s[12:13]
	v_mov_b32_e32 v104, 1.0
	s_cbranch_vccnz .LBB0_898
	v_lshl_add_u64 v[14:15], v[14:15], 2, s[22:23]
	global_load_dword v104, v[14:15], off

.LBB0_900:
	s_or_b64 exec, exec, s[24:25]
	s_and_b64 vcc, exec, s[12:13]
	v_mov_b32_e32 v106, 1.0
	s_cbranch_vccnz .LBB0_853
	v_lshl_add_u64 v[20:21], v[22:23], 2, s[22:23]
	global_load_dword v106, v[20:21], off
	s_branch .LBB0_853
